# SwiGLU epilogue: row scale 1/rs^2 = m folded into the sigmoid reciprocal (packed fma replaces packed add + packed mul)
# speedup vs baseline: 1.0032x; 1.0032x over previous
.LBB0_361:
	s_waitcnt vmcnt(0) lgkmcnt(0)
	v_mul_lo_u32 v128, v152, s42
	s_lshl_b32 s18, s47, 8
	v_lshl_add_u32 v129, v146, 1, s18
	v_add_u32_e32 v128, v128, v129
	v_fmamk_f32 v132, v167, 0x3a800000, v162
	v_cmp_gt_f32_e32 vcc, s40, v132
	v_mul_f32_e32 v133, 0x4b800000, v132
	v_cndmask_b32_e64 v134, v132, 1.0, s[14:15]
	v_pk_mul_f32 v[116:117], v[124:125], v[116:117]
	v_pk_mul_f32 v[118:119], v[126:127], v[118:119]
	v_cndmask_b32_e32 v132, v132, v133, vcc
	v_rsq_f32_e32 v132, v132
	v_pk_mul_f32 v[112:113], v[120:121], v[112:113]
	v_pk_mul_f32 v[114:115], v[122:123], v[114:115]
	v_mul_f32_e32 v133, 0x45800000, v132
	v_cndmask_b32_e32 v132, v132, v133, vcc
	v_cndmask_b32_e64 v132, v132, 1.0, s[14:15]
	v_mul_f32_e32 v130, 0xbfb8aa3b, v132
	v_pk_mul_f32 v[124:125], v[124:125], v[130:131] op_sel_hi:[1,0]
	v_pk_mul_f32 v[126:127], v[126:127], v[130:131] op_sel_hi:[1,0]
	v_pk_mul_f32 v[120:121], v[120:121], v[130:131] op_sel_hi:[1,0]
	v_pk_mul_f32 v[122:123], v[122:123], v[130:131] op_sel_hi:[1,0]
	v_exp_f32_e32 v124, v124
	v_exp_f32_e32 v125, v125
	v_exp_f32_e32 v126, v126
	v_exp_f32_e32 v127, v127
	v_exp_f32_e32 v120, v120
	v_exp_f32_e32 v121, v121
	v_exp_f32_e32 v122, v122
	v_exp_f32_e32 v123, v123
	v_pk_fma_f32 v[124:125], v[124:125], v[134:135], v[134:135] op_sel_hi:[1,0,0]
	v_pk_fma_f32 v[126:127], v[126:127], v[134:135], v[134:135] op_sel_hi:[1,0,0]
	v_pk_fma_f32 v[120:121], v[120:121], v[134:135], v[134:135] op_sel_hi:[1,0,0]
	v_pk_fma_f32 v[122:123], v[122:123], v[134:135], v[134:135] op_sel_hi:[1,0,0]
	v_rcp_f32_e32 v124, v124
	v_rcp_f32_e32 v125, v125
	v_rcp_f32_e32 v126, v126
	v_rcp_f32_e32 v127, v127
	v_rcp_f32_e32 v120, v120
	v_rcp_f32_e32 v121, v121
	v_rcp_f32_e32 v122, v122
	v_rcp_f32_e32 v123, v123
	v_pk_mul_f32 v[116:117], v[116:117], v[124:125]
	v_pk_mul_f32 v[118:119], v[118:119], v[126:127]
	v_pk_mul_f32 v[112:113], v[112:113], v[120:121]
	v_pk_mul_f32 v[114:115], v[114:115], v[122:123]
	v_cvt_pk_bf16_f32 v124, v116, v117
	v_cvt_pk_bf16_f32 v125, v118, v119
	v_cvt_pk_bf16_f32 v126, v112, v113
	v_cvt_pk_bf16_f32 v127, v114, v115
	global_store_dwordx4 v128, v[124:127], s[28:29]
	v_fmamk_f32 v132, v168, 0x3a800000, v162
	v_cmp_gt_f32_e32 vcc, s40, v132
	v_mul_f32_e32 v133, 0x4b800000, v132
	v_cndmask_b32_e64 v134, v132, 1.0, s[14:15]
	v_pk_mul_f32 v[100:101], v[108:109], v[100:101]
	v_pk_mul_f32 v[102:103], v[110:111], v[102:103]
	v_cndmask_b32_e32 v132, v132, v133, vcc
	v_rsq_f32_e32 v132, v132
	v_pk_mul_f32 v[96:97], v[104:105], v[96:97]
	v_pk_mul_f32 v[98:99], v[106:107], v[98:99]
	v_mul_f32_e32 v133, 0x45800000, v132
	v_cndmask_b32_e32 v132, v132, v133, vcc
	v_cndmask_b32_e64 v132, v132, 1.0, s[14:15]
	v_mul_f32_e32 v130, 0xbfb8aa3b, v132
	v_pk_mul_f32 v[108:109], v[108:109], v[130:131] op_sel_hi:[1,0]
	v_pk_mul_f32 v[110:111], v[110:111], v[130:131] op_sel_hi:[1,0]
	v_pk_mul_f32 v[104:105], v[104:105], v[130:131] op_sel_hi:[1,0]
	v_pk_mul_f32 v[106:107], v[106:107], v[130:131] op_sel_hi:[1,0]
	v_exp_f32_e32 v108, v108
	v_exp_f32_e32 v109, v109
	v_exp_f32_e32 v110, v110
	v_exp_f32_e32 v111, v111
	v_exp_f32_e32 v104, v104
	v_exp_f32_e32 v105, v105
	v_exp_f32_e32 v106, v106
	v_exp_f32_e32 v107, v107
	v_pk_fma_f32 v[108:109], v[108:109], v[134:135], v[134:135] op_sel_hi:[1,0,0]
	v_pk_fma_f32 v[110:111], v[110:111], v[134:135], v[134:135] op_sel_hi:[1,0,0]
	v_pk_fma_f32 v[104:105], v[104:105], v[134:135], v[134:135] op_sel_hi:[1,0,0]
	v_pk_fma_f32 v[106:107], v[106:107], v[134:135], v[134:135] op_sel_hi:[1,0,0]
	v_rcp_f32_e32 v108, v108
	v_rcp_f32_e32 v109, v109
	v_rcp_f32_e32 v110, v110
	v_rcp_f32_e32 v111, v111
	v_rcp_f32_e32 v104, v104
	v_rcp_f32_e32 v105, v105
	v_rcp_f32_e32 v106, v106
	v_rcp_f32_e32 v107, v107
	v_pk_mul_f32 v[100:101], v[100:101], v[108:109]
	v_pk_mul_f32 v[102:103], v[102:103], v[110:111]
	v_pk_mul_f32 v[96:97], v[96:97], v[104:105]
	v_pk_mul_f32 v[98:99], v[98:99], v[106:107]
	v_add_u32_e32 v129, 0x16000, v128
	v_cvt_pk_bf16_f32 v108, v100, v101
	v_cvt_pk_bf16_f32 v109, v102, v103
	v_cvt_pk_bf16_f32 v110, v96, v97
	v_cvt_pk_bf16_f32 v111, v98, v99
	global_store_dwordx4 v129, v[108:111], s[28:29]
	v_fmamk_f32 v132, v169, 0x3a800000, v162
	v_cmp_gt_f32_e32 vcc, s40, v132
	v_mul_f32_e32 v133, 0x4b800000, v132
	v_cndmask_b32_e64 v134, v132, 1.0, s[14:15]
	v_pk_mul_f32 v[84:85], v[92:93], v[84:85]
	v_pk_mul_f32 v[86:87], v[94:95], v[86:87]
	v_cndmask_b32_e32 v132, v132, v133, vcc
	v_rsq_f32_e32 v132, v132
	v_pk_mul_f32 v[80:81], v[88:89], v[80:81]
	v_pk_mul_f32 v[82:83], v[90:91], v[82:83]
	v_mul_f32_e32 v133, 0x45800000, v132
	v_cndmask_b32_e32 v132, v132, v133, vcc
	v_cndmask_b32_e64 v132, v132, 1.0, s[14:15]
	v_mul_f32_e32 v130, 0xbfb8aa3b, v132
	v_pk_mul_f32 v[92:93], v[92:93], v[130:131] op_sel_hi:[1,0]
	v_pk_mul_f32 v[94:95], v[94:95], v[130:131] op_sel_hi:[1,0]
	v_pk_mul_f32 v[88:89], v[88:89], v[130:131] op_sel_hi:[1,0]
	v_pk_mul_f32 v[90:91], v[90:91], v[130:131] op_sel_hi:[1,0]
	v_exp_f32_e32 v92, v92
	v_exp_f32_e32 v93, v93
	v_exp_f32_e32 v94, v94
	v_exp_f32_e32 v95, v95
	v_exp_f32_e32 v88, v88
	v_exp_f32_e32 v89, v89
	v_exp_f32_e32 v90, v90
	v_exp_f32_e32 v91, v91
	v_pk_fma_f32 v[92:93], v[92:93], v[134:135], v[134:135] op_sel_hi:[1,0,0]
	v_pk_fma_f32 v[94:95], v[94:95], v[134:135], v[134:135] op_sel_hi:[1,0,0]
	v_pk_fma_f32 v[88:89], v[88:89], v[134:135], v[134:135] op_sel_hi:[1,0,0]
	v_pk_fma_f32 v[90:91], v[90:91], v[134:135], v[134:135] op_sel_hi:[1,0,0]
	v_rcp_f32_e32 v92, v92
	v_rcp_f32_e32 v93, v93
	v_rcp_f32_e32 v94, v94
	v_rcp_f32_e32 v95, v95
	v_rcp_f32_e32 v88, v88
	v_rcp_f32_e32 v89, v89
	v_rcp_f32_e32 v90, v90
	v_rcp_f32_e32 v91, v91
	v_pk_mul_f32 v[84:85], v[84:85], v[92:93]
	v_pk_mul_f32 v[86:87], v[86:87], v[94:95]
	v_pk_mul_f32 v[80:81], v[80:81], v[88:89]
	v_pk_mul_f32 v[82:83], v[82:83], v[90:91]
	v_add_u32_e32 v129, 0x2c000, v128
	v_cvt_pk_bf16_f32 v92, v84, v85
	v_cvt_pk_bf16_f32 v93, v86, v87
	v_cvt_pk_bf16_f32 v94, v80, v81
	v_cvt_pk_bf16_f32 v95, v82, v83
	global_store_dwordx4 v129, v[92:95], s[28:29]
	v_fmamk_f32 v132, v170, 0x3a800000, v162
	v_cmp_gt_f32_e32 vcc, s40, v132
	v_mul_f32_e32 v133, 0x4b800000, v132
	v_cndmask_b32_e64 v134, v132, 1.0, s[14:15]
	v_pk_mul_f32 v[68:69], v[76:77], v[68:69]
	v_pk_mul_f32 v[70:71], v[78:79], v[70:71]
	v_cndmask_b32_e32 v132, v132, v133, vcc
	v_rsq_f32_e32 v132, v132
	v_pk_mul_f32 v[64:65], v[72:73], v[64:65]
	v_pk_mul_f32 v[66:67], v[74:75], v[66:67]
	v_mul_f32_e32 v133, 0x45800000, v132
	v_cndmask_b32_e32 v132, v132, v133, vcc
	v_cndmask_b32_e64 v132, v132, 1.0, s[14:15]
	v_mul_f32_e32 v130, 0xbfb8aa3b, v132
	v_pk_mul_f32 v[76:77], v[76:77], v[130:131] op_sel_hi:[1,0]
	v_pk_mul_f32 v[78:79], v[78:79], v[130:131] op_sel_hi:[1,0]
	v_pk_mul_f32 v[72:73], v[72:73], v[130:131] op_sel_hi:[1,0]
	v_pk_mul_f32 v[74:75], v[74:75], v[130:131] op_sel_hi:[1,0]
	v_exp_f32_e32 v76, v76
	v_exp_f32_e32 v77, v77
	v_exp_f32_e32 v78, v78
	v_exp_f32_e32 v79, v79
	v_exp_f32_e32 v72, v72
	v_exp_f32_e32 v73, v73
	v_exp_f32_e32 v74, v74
	v_exp_f32_e32 v75, v75
	v_pk_fma_f32 v[76:77], v[76:77], v[134:135], v[134:135] op_sel_hi:[1,0,0]
	v_pk_fma_f32 v[78:79], v[78:79], v[134:135], v[134:135] op_sel_hi:[1,0,0]
	v_pk_fma_f32 v[72:73], v[72:73], v[134:135], v[134:135] op_sel_hi:[1,0,0]
	v_pk_fma_f32 v[74:75], v[74:75], v[134:135], v[134:135] op_sel_hi:[1,0,0]
	v_rcp_f32_e32 v76, v76
	v_rcp_f32_e32 v77, v77
	v_rcp_f32_e32 v78, v78
	v_rcp_f32_e32 v79, v79
	v_rcp_f32_e32 v72, v72
	v_rcp_f32_e32 v73, v73
	v_rcp_f32_e32 v74, v74
	v_rcp_f32_e32 v75, v75
	v_pk_mul_f32 v[68:69], v[68:69], v[76:77]
	v_pk_mul_f32 v[70:71], v[70:71], v[78:79]
	v_pk_mul_f32 v[64:65], v[64:65], v[72:73]
	v_pk_mul_f32 v[66:67], v[66:67], v[74:75]
	v_add_u32_e32 v129, 0x42000, v128
	v_cvt_pk_bf16_f32 v76, v68, v69
	v_cvt_pk_bf16_f32 v77, v70, v71
	v_cvt_pk_bf16_f32 v78, v64, v65
	v_cvt_pk_bf16_f32 v79, v66, v67
	global_store_dwordx4 v129, v[76:79], s[28:29]
	v_fmamk_f32 v132, v171, 0x3a800000, v162
	v_cmp_gt_f32_e32 vcc, s40, v132
	v_mul_f32_e32 v133, 0x4b800000, v132
	v_cndmask_b32_e64 v134, v132, 1.0, s[14:15]
	v_pk_mul_f32 v[52:53], v[60:61], v[52:53]
	v_pk_mul_f32 v[54:55], v[62:63], v[54:55]
	v_cndmask_b32_e32 v132, v132, v133, vcc
	v_rsq_f32_e32 v132, v132
	v_pk_mul_f32 v[48:49], v[56:57], v[48:49]
	v_pk_mul_f32 v[50:51], v[58:59], v[50:51]
	v_mul_f32_e32 v133, 0x45800000, v132
	v_cndmask_b32_e32 v132, v132, v133, vcc
	v_cndmask_b32_e64 v132, v132, 1.0, s[14:15]
	v_mul_f32_e32 v130, 0xbfb8aa3b, v132
	v_pk_mul_f32 v[60:61], v[60:61], v[130:131] op_sel_hi:[1,0]
	v_pk_mul_f32 v[62:63], v[62:63], v[130:131] op_sel_hi:[1,0]
	v_pk_mul_f32 v[56:57], v[56:57], v[130:131] op_sel_hi:[1,0]
	v_pk_mul_f32 v[58:59], v[58:59], v[130:131] op_sel_hi:[1,0]
	v_exp_f32_e32 v60, v60
	v_exp_f32_e32 v61, v61
	v_exp_f32_e32 v62, v62
	v_exp_f32_e32 v63, v63
	v_exp_f32_e32 v56, v56
	v_exp_f32_e32 v57, v57
	v_exp_f32_e32 v58, v58
	v_exp_f32_e32 v59, v59
	v_pk_fma_f32 v[60:61], v[60:61], v[134:135], v[134:135] op_sel_hi:[1,0,0]
	v_pk_fma_f32 v[62:63], v[62:63], v[134:135], v[134:135] op_sel_hi:[1,0,0]
	v_pk_fma_f32 v[56:57], v[56:57], v[134:135], v[134:135] op_sel_hi:[1,0,0]
	v_pk_fma_f32 v[58:59], v[58:59], v[134:135], v[134:135] op_sel_hi:[1,0,0]
	v_rcp_f32_e32 v60, v60
	v_rcp_f32_e32 v61, v61
	v_rcp_f32_e32 v62, v62
	v_rcp_f32_e32 v63, v63
	v_rcp_f32_e32 v56, v56
	v_rcp_f32_e32 v57, v57
	v_rcp_f32_e32 v58, v58
	v_rcp_f32_e32 v59, v59
	v_pk_mul_f32 v[52:53], v[52:53], v[60:61]
	v_pk_mul_f32 v[54:55], v[54:55], v[62:63]
	v_pk_mul_f32 v[48:49], v[48:49], v[56:57]
	v_pk_mul_f32 v[50:51], v[50:51], v[58:59]
	v_add_u32_e32 v129, 0xb0000, v128
	v_cvt_pk_bf16_f32 v60, v52, v53
	v_cvt_pk_bf16_f32 v61, v54, v55
	v_cvt_pk_bf16_f32 v62, v48, v49
	v_cvt_pk_bf16_f32 v63, v50, v51
	global_store_dwordx4 v129, v[60:63], s[28:29]
	v_fmamk_f32 v132, v172, 0x3a800000, v162
	v_cmp_gt_f32_e32 vcc, s40, v132
	v_mul_f32_e32 v133, 0x4b800000, v132
	v_cndmask_b32_e64 v134, v132, 1.0, s[14:15]
	v_pk_mul_f32 v[36:37], v[44:45], v[36:37]
	v_pk_mul_f32 v[38:39], v[46:47], v[38:39]
	v_cndmask_b32_e32 v132, v132, v133, vcc
	v_rsq_f32_e32 v132, v132
	v_pk_mul_f32 v[32:33], v[40:41], v[32:33]
	v_pk_mul_f32 v[34:35], v[42:43], v[34:35]
	v_mul_f32_e32 v133, 0x45800000, v132
	v_cndmask_b32_e32 v132, v132, v133, vcc
	v_cndmask_b32_e64 v132, v132, 1.0, s[14:15]
	v_mul_f32_e32 v130, 0xbfb8aa3b, v132
	v_pk_mul_f32 v[44:45], v[44:45], v[130:131] op_sel_hi:[1,0]
	v_pk_mul_f32 v[46:47], v[46:47], v[130:131] op_sel_hi:[1,0]
	v_pk_mul_f32 v[40:41], v[40:41], v[130:131] op_sel_hi:[1,0]
	v_pk_mul_f32 v[42:43], v[42:43], v[130:131] op_sel_hi:[1,0]
	v_exp_f32_e32 v44, v44
	v_exp_f32_e32 v45, v45
	v_exp_f32_e32 v46, v46
	v_exp_f32_e32 v47, v47
	v_exp_f32_e32 v40, v40
	v_exp_f32_e32 v41, v41
	v_exp_f32_e32 v42, v42
	v_exp_f32_e32 v43, v43
	v_pk_fma_f32 v[44:45], v[44:45], v[134:135], v[134:135] op_sel_hi:[1,0,0]
	v_pk_fma_f32 v[46:47], v[46:47], v[134:135], v[134:135] op_sel_hi:[1,0,0]
	v_pk_fma_f32 v[40:41], v[40:41], v[134:135], v[134:135] op_sel_hi:[1,0,0]
	v_pk_fma_f32 v[42:43], v[42:43], v[134:135], v[134:135] op_sel_hi:[1,0,0]
	v_rcp_f32_e32 v44, v44
	v_rcp_f32_e32 v45, v45
	v_rcp_f32_e32 v46, v46
	v_rcp_f32_e32 v47, v47
	v_rcp_f32_e32 v40, v40
	v_rcp_f32_e32 v41, v41
	v_rcp_f32_e32 v42, v42
	v_rcp_f32_e32 v43, v43
	v_pk_mul_f32 v[36:37], v[36:37], v[44:45]
	v_pk_mul_f32 v[38:39], v[38:39], v[46:47]
	v_pk_mul_f32 v[32:33], v[32:33], v[40:41]
	v_pk_mul_f32 v[34:35], v[34:35], v[42:43]
	v_add_u32_e32 v129, 0xc6000, v128
	v_cvt_pk_bf16_f32 v44, v36, v37
	v_cvt_pk_bf16_f32 v45, v38, v39
	v_cvt_pk_bf16_f32 v46, v32, v33
	v_cvt_pk_bf16_f32 v47, v34, v35
	global_store_dwordx4 v129, v[44:47], s[28:29]
	v_fmamk_f32 v132, v174, 0x3a800000, v162
	v_cmp_gt_f32_e32 vcc, s40, v132
	v_mul_f32_e32 v133, 0x4b800000, v132
	v_cndmask_b32_e64 v134, v132, 1.0, s[14:15]
	v_pk_mul_f32 v[20:21], v[28:29], v[20:21]
	v_pk_mul_f32 v[22:23], v[30:31], v[22:23]
	v_cndmask_b32_e32 v132, v132, v133, vcc
	v_rsq_f32_e32 v132, v132
	v_pk_mul_f32 v[16:17], v[24:25], v[16:17]
	v_pk_mul_f32 v[18:19], v[26:27], v[18:19]
	v_mul_f32_e32 v133, 0x45800000, v132
	v_cndmask_b32_e32 v132, v132, v133, vcc
	v_cndmask_b32_e64 v132, v132, 1.0, s[14:15]
	v_mul_f32_e32 v130, 0xbfb8aa3b, v132
	v_pk_mul_f32 v[28:29], v[28:29], v[130:131] op_sel_hi:[1,0]
	v_pk_mul_f32 v[30:31], v[30:31], v[130:131] op_sel_hi:[1,0]
	v_pk_mul_f32 v[24:25], v[24:25], v[130:131] op_sel_hi:[1,0]
	v_pk_mul_f32 v[26:27], v[26:27], v[130:131] op_sel_hi:[1,0]
	v_exp_f32_e32 v28, v28
	v_exp_f32_e32 v29, v29
	v_exp_f32_e32 v30, v30
	v_exp_f32_e32 v31, v31
	v_exp_f32_e32 v24, v24
	v_exp_f32_e32 v25, v25
	v_exp_f32_e32 v26, v26
	v_exp_f32_e32 v27, v27
	v_pk_fma_f32 v[28:29], v[28:29], v[134:135], v[134:135] op_sel_hi:[1,0,0]
	v_pk_fma_f32 v[30:31], v[30:31], v[134:135], v[134:135] op_sel_hi:[1,0,0]
	v_pk_fma_f32 v[24:25], v[24:25], v[134:135], v[134:135] op_sel_hi:[1,0,0]
	v_pk_fma_f32 v[26:27], v[26:27], v[134:135], v[134:135] op_sel_hi:[1,0,0]
	v_rcp_f32_e32 v28, v28
	v_rcp_f32_e32 v29, v29
	v_rcp_f32_e32 v30, v30
	v_rcp_f32_e32 v31, v31
	v_rcp_f32_e32 v24, v24
	v_rcp_f32_e32 v25, v25
	v_rcp_f32_e32 v26, v26
	v_rcp_f32_e32 v27, v27
	v_pk_mul_f32 v[20:21], v[20:21], v[28:29]
	v_pk_mul_f32 v[22:23], v[22:23], v[30:31]
	v_pk_mul_f32 v[16:17], v[16:17], v[24:25]
	v_pk_mul_f32 v[18:19], v[18:19], v[26:27]
	v_add_u32_e32 v129, 0xdc000, v128
	v_cvt_pk_bf16_f32 v28, v20, v21
	v_cvt_pk_bf16_f32 v29, v22, v23
	v_cvt_pk_bf16_f32 v30, v16, v17
	v_cvt_pk_bf16_f32 v31, v18, v19
	global_store_dwordx4 v129, v[28:31], s[28:29]
	v_fmamk_f32 v132, v173, 0x3a800000, v162
	v_cmp_gt_f32_e32 vcc, s40, v132
	v_mul_f32_e32 v133, 0x4b800000, v132
	v_cndmask_b32_e64 v134, v132, 1.0, s[14:15]
	v_pk_mul_f32 v[4:5], v[12:13], v[4:5]
	v_pk_mul_f32 v[6:7], v[14:15], v[6:7]
	v_cndmask_b32_e32 v132, v132, v133, vcc
	v_rsq_f32_e32 v132, v132
	v_pk_mul_f32 v[0:1], v[8:9], v[0:1]
	v_pk_mul_f32 v[2:3], v[10:11], v[2:3]
	v_mul_f32_e32 v133, 0x45800000, v132
	v_cndmask_b32_e32 v132, v132, v133, vcc
	v_cndmask_b32_e64 v132, v132, 1.0, s[14:15]
	v_mul_f32_e32 v130, 0xbfb8aa3b, v132
	v_pk_mul_f32 v[12:13], v[12:13], v[130:131] op_sel_hi:[1,0]
	v_pk_mul_f32 v[14:15], v[14:15], v[130:131] op_sel_hi:[1,0]
	v_pk_mul_f32 v[8:9], v[8:9], v[130:131] op_sel_hi:[1,0]
	v_pk_mul_f32 v[10:11], v[10:11], v[130:131] op_sel_hi:[1,0]
	v_exp_f32_e32 v12, v12
	v_exp_f32_e32 v13, v13
	v_exp_f32_e32 v14, v14
	v_exp_f32_e32 v15, v15
	v_exp_f32_e32 v8, v8
	v_exp_f32_e32 v9, v9
	v_exp_f32_e32 v10, v10
	v_exp_f32_e32 v11, v11
	v_pk_fma_f32 v[12:13], v[12:13], v[134:135], v[134:135] op_sel_hi:[1,0,0]
	v_pk_fma_f32 v[14:15], v[14:15], v[134:135], v[134:135] op_sel_hi:[1,0,0]
	v_pk_fma_f32 v[8:9], v[8:9], v[134:135], v[134:135] op_sel_hi:[1,0,0]
	v_pk_fma_f32 v[10:11], v[10:11], v[134:135], v[134:135] op_sel_hi:[1,0,0]
	v_rcp_f32_e32 v12, v12
	v_rcp_f32_e32 v13, v13
	v_rcp_f32_e32 v14, v14
	v_rcp_f32_e32 v15, v15
	v_rcp_f32_e32 v8, v8
	v_rcp_f32_e32 v9, v9
	v_rcp_f32_e32 v10, v10
	v_rcp_f32_e32 v11, v11
	v_pk_mul_f32 v[4:5], v[4:5], v[12:13]
	v_pk_mul_f32 v[6:7], v[6:7], v[14:15]
	v_pk_mul_f32 v[0:1], v[0:1], v[8:9]
	v_pk_mul_f32 v[2:3], v[2:3], v[10:11]
	v_add_u32_e32 v129, 0xf2000, v128
	v_cvt_pk_bf16_f32 v12, v4, v5
	v_cvt_pk_bf16_f32 v13, v6, v7
	v_cvt_pk_bf16_f32 v14, v0, v1
	v_cvt_pk_bf16_f32 v15, v2, v3
	global_store_dwordx4 v129, v[12:15], s[28:29]
	s_and_b64 vcc, exec, s[38:39]
	s_cbranch_vccz .LBB0_158
